# P7 epilogue: hoist the 8 per-row rs loads ahead of the stores, one wait instead of 8
# baseline (speedup 1.0000x reference)
; __device__ __forceinline__ unsigned pk2(float lo, float hi) { f32x2 v = {lo, hi}; bf16x2_t b = __builtin_convertvector(v, bf16x2_t); return __builtin_bit_cast(unsigned, b); }
;     __device__ __forceinline__ void operator()(const f32x4 (&acc)[2][2][4][2], const Unit& u, int wr, int wc, int fr, int fq) const {
;         const int row0 = u.pm * BM + wr * 64 + fr; const int col0 = u.pn * BM + wc * 32 + 8 * fq;
; #pragma unroll
;         for (int ai = 0; ai < 2; ++ai)
; #pragma unroll
;             for (int m = 0; m < 4; ++m) { bf16_t* rowp = O + (size_t)(row0 + ai * HALF + m * 16) * ldc + col0; float rsv = 1.f; if (ACT == 1) rsv = rs[row0 + ai * HALF + m * 16];
; #pragma unroll
;                 for (int bj = 0; bj < 2; ++bj) { f32x4 v0 = acc[ai][bj][m][0], v1 = acc[ai][bj][m][1];
;                     if (ACT == 1) {
; #pragma unroll
;                         for (int j = 0; j < 4; ++j) { const float a = fmaxf(v0[j] * rsv, 0.f), b = fmaxf(v1[j] * rsv, 0.f); v0[j] = a * a; v1[j] = b * b; } }
;                     u32x4 w; w.x = pk2(v0[0], v0[1]); w.y = pk2(v0[2], v0[3]); w.z = pk2(v1[0], v1[1]); w.w = pk2(v1[2], v1[3]);
;                     *(u32x4*)(rowp + bj * HALF) = w; } }
.LBB0_1221:
	v_mov_b32_e32 v138, v206
	s_lshl_b32 s0, s22, 8
	s_add_i32 s0, s0, s60
	v_and_or_b32 v142, v138, 15, s0
	s_lshl_b32 s0, s8, 8
	v_lshrrev_b32_e32 v138, 1, v138
	v_and_or_b32 v138, v138, 24, s0
	v_or_b32_e32 v138, s61, v138
	v_ashrrev_i32_e32 v143, 31, v142
	v_ashrrev_i32_e32 v139, 31, v138
	v_lshlrev_b64 v[140:141], 13, v[142:143]
	v_lshl_add_u64 v[140:141], s[34:35], 0, v[140:141]
	v_lshlrev_b64 v[144:145], 1, v[138:139]
	v_lshl_add_u64 v[138:139], v[140:141], 0, v[144:145]
	v_lshl_add_u64 v[140:141], v[142:143], 2, s[40:41]
	flat_load_dword v143, v[140:141]
	flat_load_dword v214, v[140:141] offset:64
	flat_load_dword v215, v[140:141] offset:128
	flat_load_dword v216, v[140:141] offset:192
	flat_load_dword v217, v[140:141] offset:512
	flat_load_dword v218, v[140:141] offset:576
	flat_load_dword v219, v[140:141] offset:640
	flat_load_dword v220, v[140:141] offset:704
	s_mov_b64 s[0:1], 0x100000
	s_mov_b64 s[22:23], -1
	s_waitcnt vmcnt(0) lgkmcnt(0)
	v_mul_f32_e32 v120, v120, v143
	v_mul_f32_e32 v121, v121, v143
	v_max_f32_e32 v120, 0, v120
	v_max_f32_e32 v121, 0, v121
	v_pk_mul_f32 v[148:149], v[120:121], v[120:121]
	v_mul_f32_e32 v121, v122, v143
	v_mul_f32_e32 v124, v124, v143
	v_mul_f32_e32 v125, v125, v143
	v_mul_f32_e32 v120, v126, v143
	v_max_f32_e32 v122, 0, v121
	v_mul_f32_e32 v121, v127, v143
	v_mul_f32_e32 v123, v123, v143
	v_max_f32_e32 v124, 0, v124
	v_max_f32_e32 v125, 0, v125
	v_max_f32_e32 v120, 0, v120
	v_max_f32_e32 v121, 0, v121
	v_max_f32_e32 v123, 0, v123
	v_pk_mul_f32 v[124:125], v[124:125], v[124:125]
	v_pk_mul_f32 v[126:127], v[120:121], v[120:121]
	v_pk_mul_f32 v[150:151], v[122:123], v[122:123]
	v_mul_f32_e32 v112, v112, v143
	v_mul_f32_e32 v113, v113, v143
	v_cvt_pk_bf16_f32 v120, v124, v125
	v_cvt_pk_bf16_f32 v121, v126, v127
	v_cvt_pk_bf16_f32 v122, v148, v149
	v_cvt_pk_bf16_f32 v123, v150, v151
	v_max_f32_e32 v112, 0, v112
	v_max_f32_e32 v113, 0, v113
	flat_store_dwordx4 v[138:139], v[120:123]
	v_mul_f32_e32 v116, v116, v143
	v_mul_f32_e32 v117, v117, v143
	v_pk_mul_f32 v[120:121], v[112:113], v[112:113]
	v_mul_f32_e32 v113, v114, v143
	v_mul_f32_e32 v112, v118, v143
	v_max_f32_e32 v114, 0, v113
	v_mul_f32_e32 v113, v119, v143
	v_mul_f32_e32 v115, v115, v143
	v_max_f32_e32 v116, 0, v116
	v_max_f32_e32 v117, 0, v117
	v_max_f32_e32 v112, 0, v112
	v_max_f32_e32 v113, 0, v113
	v_max_f32_e32 v115, 0, v115
	v_pk_mul_f32 v[116:117], v[116:117], v[116:117]
	v_pk_mul_f32 v[118:119], v[112:113], v[112:113]
	v_pk_mul_f32 v[122:123], v[114:115], v[114:115]
	v_cvt_pk_bf16_f32 v112, v116, v117
	v_cvt_pk_bf16_f32 v113, v118, v119
	v_cvt_pk_bf16_f32 v114, v120, v121
	v_cvt_pk_bf16_f32 v115, v122, v123
	flat_store_dwordx4 v[138:139], v[112:115] offset:256
	s_nop 1
	v_or_b32_e32 v114, 16, v142
	v_ashrrev_i32_e32 v115, 31, v114
	v_lshlrev_b64 v[112:113], 13, v[114:115]
	v_lshl_add_u64 v[114:115], v[114:115], 2, s[40:41]
	v_mov_b32_e32 v118, v214
	v_lshl_add_u64 v[112:113], s[34:35], 0, v[112:113]
	v_lshl_add_u64 v[112:113], v[112:113], 0, v[144:145]
	v_mul_f32_e32 v104, v104, v118
	v_mul_f32_e32 v105, v105, v118
	v_max_f32_e32 v104, 0, v104
	v_max_f32_e32 v105, 0, v105
	v_pk_mul_f32 v[114:115], v[104:105], v[104:105]
	v_mul_f32_e32 v105, v106, v118
	v_mul_f32_e32 v108, v108, v118
	v_mul_f32_e32 v109, v109, v118
	v_mul_f32_e32 v104, v110, v118
	v_max_f32_e32 v106, 0, v105
	v_mul_f32_e32 v105, v111, v118
	v_mul_f32_e32 v107, v107, v118
	v_max_f32_e32 v108, 0, v108
	v_max_f32_e32 v109, 0, v109
	v_max_f32_e32 v104, 0, v104
	v_max_f32_e32 v105, 0, v105
	v_max_f32_e32 v107, 0, v107
	v_pk_mul_f32 v[108:109], v[108:109], v[108:109]
	v_pk_mul_f32 v[110:111], v[104:105], v[104:105]
	v_pk_mul_f32 v[116:117], v[106:107], v[106:107]
	v_mul_f32_e32 v96, v96, v118
	v_mul_f32_e32 v97, v97, v118
	v_cvt_pk_bf16_f32 v104, v108, v109
	v_cvt_pk_bf16_f32 v105, v110, v111
	v_cvt_pk_bf16_f32 v106, v114, v115
	v_cvt_pk_bf16_f32 v107, v116, v117
	v_max_f32_e32 v96, 0, v96
	v_max_f32_e32 v97, 0, v97
	flat_store_dwordx4 v[112:113], v[104:107]
	v_mul_f32_e32 v100, v100, v118
	v_mul_f32_e32 v101, v101, v118
	v_pk_mul_f32 v[104:105], v[96:97], v[96:97]
	v_mul_f32_e32 v97, v98, v118
	v_mul_f32_e32 v96, v102, v118
	v_max_f32_e32 v98, 0, v97
	v_mul_f32_e32 v97, v103, v118
	v_mul_f32_e32 v99, v99, v118
	v_max_f32_e32 v100, 0, v100
	v_max_f32_e32 v101, 0, v101
	v_max_f32_e32 v96, 0, v96
	v_max_f32_e32 v97, 0, v97
	v_max_f32_e32 v99, 0, v99
	v_pk_mul_f32 v[100:101], v[100:101], v[100:101]
	v_pk_mul_f32 v[102:103], v[96:97], v[96:97]
	v_pk_mul_f32 v[106:107], v[98:99], v[98:99]
	v_cvt_pk_bf16_f32 v96, v100, v101
	v_cvt_pk_bf16_f32 v97, v102, v103
	v_cvt_pk_bf16_f32 v98, v104, v105
	v_cvt_pk_bf16_f32 v99, v106, v107
	flat_store_dwordx4 v[112:113], v[96:99] offset:256
	s_nop 1
	v_or_b32_e32 v98, 32, v142
	v_ashrrev_i32_e32 v99, 31, v98
	v_lshlrev_b64 v[96:97], 13, v[98:99]
	v_lshl_add_u64 v[98:99], v[98:99], 2, s[40:41]
	v_mov_b32_e32 v102, v215
	v_lshl_add_u64 v[96:97], s[34:35], 0, v[96:97]
	v_lshl_add_u64 v[96:97], v[96:97], 0, v[144:145]
	v_mul_f32_e32 v88, v88, v102
	v_mul_f32_e32 v89, v89, v102
	v_max_f32_e32 v88, 0, v88
	v_max_f32_e32 v89, 0, v89
	v_pk_mul_f32 v[98:99], v[88:89], v[88:89]
	v_mul_f32_e32 v89, v90, v102
	v_mul_f32_e32 v92, v92, v102
	v_mul_f32_e32 v93, v93, v102
	v_mul_f32_e32 v88, v94, v102
	v_max_f32_e32 v90, 0, v89
	v_mul_f32_e32 v89, v95, v102
	v_mul_f32_e32 v91, v91, v102
	v_max_f32_e32 v92, 0, v92
	v_max_f32_e32 v93, 0, v93
	v_max_f32_e32 v88, 0, v88
	v_max_f32_e32 v89, 0, v89
	v_max_f32_e32 v91, 0, v91
	v_pk_mul_f32 v[92:93], v[92:93], v[92:93]
	v_pk_mul_f32 v[94:95], v[88:89], v[88:89]
	v_pk_mul_f32 v[100:101], v[90:91], v[90:91]
; __device__ __forceinline__ unsigned pk2(float lo, float hi) { f32x2 v = {lo, hi}; bf16x2_t b = __builtin_convertvector(v, bf16x2_t); return __builtin_bit_cast(unsigned, b); }
;     __device__ __forceinline__ void operator()(const f32x4 (&acc)[2][2][4][2], const Unit& u, int wr, int wc, int fr, int fq) const {
;     ...
;             for (int m = 0; m < 4; ++m) { bf16_t* rowp = O + (size_t)(row0 + ai * HALF + m * 16) * ldc + col0; float rsv = 1.f; if (ACT == 1) rsv = rs[row0 + ai * HALF + m * 16];
; #pragma unroll
;                 for (int bj = 0; bj < 2; ++bj) { f32x4 v0 = acc[ai][bj][m][0], v1 = acc[ai][bj][m][1];
;                     if (ACT == 1) {
; #pragma unroll
;                         for (int j = 0; j < 4; ++j) { const float a = fmaxf(v0[j] * rsv, 0.f), b = fmaxf(v1[j] * rsv, 0.f); v0[j] = a * a; v1[j] = b * b; } }
;                     u32x4 w; w.x = pk2(v0[0], v0[1]); w.y = pk2(v0[2], v0[3]); w.z = pk2(v1[0], v1[1]); w.w = pk2(v1[2], v1[3]);
;                     *(u32x4*)(rowp + bj * HALF) = w; } }
	v_mul_f32_e32 v80, v80, v102
	v_mul_f32_e32 v81, v81, v102
	v_cvt_pk_bf16_f32 v88, v92, v93
	v_cvt_pk_bf16_f32 v89, v94, v95
	v_cvt_pk_bf16_f32 v90, v98, v99
	v_cvt_pk_bf16_f32 v91, v100, v101
	v_max_f32_e32 v80, 0, v80
	v_max_f32_e32 v81, 0, v81
	flat_store_dwordx4 v[96:97], v[88:91]
	v_mul_f32_e32 v84, v84, v102
	v_mul_f32_e32 v85, v85, v102
	v_pk_mul_f32 v[88:89], v[80:81], v[80:81]
	v_mul_f32_e32 v81, v82, v102
	v_mul_f32_e32 v80, v86, v102
	v_max_f32_e32 v82, 0, v81
	v_mul_f32_e32 v81, v87, v102
	v_mul_f32_e32 v83, v83, v102
	v_max_f32_e32 v84, 0, v84
	v_max_f32_e32 v85, 0, v85
	v_max_f32_e32 v80, 0, v80
	v_max_f32_e32 v81, 0, v81
	v_max_f32_e32 v83, 0, v83
	v_pk_mul_f32 v[84:85], v[84:85], v[84:85]
	v_pk_mul_f32 v[86:87], v[80:81], v[80:81]
	v_pk_mul_f32 v[90:91], v[82:83], v[82:83]
	v_cvt_pk_bf16_f32 v80, v84, v85
	v_cvt_pk_bf16_f32 v81, v86, v87
	v_cvt_pk_bf16_f32 v82, v88, v89
	v_cvt_pk_bf16_f32 v83, v90, v91
	flat_store_dwordx4 v[96:97], v[80:83] offset:256
	s_nop 1
	v_or_b32_e32 v82, 48, v142
	v_ashrrev_i32_e32 v83, 31, v82
	v_lshlrev_b64 v[80:81], 13, v[82:83]
	v_lshl_add_u64 v[82:83], v[82:83], 2, s[40:41]
	v_mov_b32_e32 v86, v216
	v_lshl_add_u64 v[80:81], s[34:35], 0, v[80:81]
	v_lshl_add_u64 v[80:81], v[80:81], 0, v[144:145]
	v_mul_f32_e32 v72, v72, v86
	v_mul_f32_e32 v73, v73, v86
	v_max_f32_e32 v72, 0, v72
	v_max_f32_e32 v73, 0, v73
	v_pk_mul_f32 v[82:83], v[72:73], v[72:73]
	v_mul_f32_e32 v73, v74, v86
	v_mul_f32_e32 v76, v76, v86
	v_mul_f32_e32 v77, v77, v86
	v_mul_f32_e32 v72, v78, v86
	v_max_f32_e32 v74, 0, v73
	v_mul_f32_e32 v73, v79, v86
	v_mul_f32_e32 v75, v75, v86
	v_max_f32_e32 v76, 0, v76
	v_max_f32_e32 v77, 0, v77
	v_max_f32_e32 v72, 0, v72
	v_max_f32_e32 v73, 0, v73
	v_max_f32_e32 v75, 0, v75
	v_pk_mul_f32 v[76:77], v[76:77], v[76:77]
	v_pk_mul_f32 v[78:79], v[72:73], v[72:73]
	v_pk_mul_f32 v[84:85], v[74:75], v[74:75]
	v_mul_f32_e32 v64, v64, v86
	v_mul_f32_e32 v65, v65, v86
	v_cvt_pk_bf16_f32 v72, v76, v77
	v_cvt_pk_bf16_f32 v73, v78, v79
	v_cvt_pk_bf16_f32 v74, v82, v83
	v_cvt_pk_bf16_f32 v75, v84, v85
	v_max_f32_e32 v64, 0, v64
	v_max_f32_e32 v65, 0, v65
	flat_store_dwordx4 v[80:81], v[72:75]
	v_mul_f32_e32 v68, v68, v86
	v_mul_f32_e32 v69, v69, v86
	v_pk_mul_f32 v[72:73], v[64:65], v[64:65]
	v_mul_f32_e32 v65, v66, v86
	v_mul_f32_e32 v64, v70, v86
	v_max_f32_e32 v66, 0, v65
	v_mul_f32_e32 v65, v71, v86
	v_mul_f32_e32 v67, v67, v86
	v_max_f32_e32 v68, 0, v68
	v_max_f32_e32 v69, 0, v69
	v_max_f32_e32 v64, 0, v64
	v_max_f32_e32 v65, 0, v65
	v_max_f32_e32 v67, 0, v67
	v_pk_mul_f32 v[68:69], v[68:69], v[68:69]
	v_pk_mul_f32 v[70:71], v[64:65], v[64:65]
	v_pk_mul_f32 v[74:75], v[66:67], v[66:67]
	v_cvt_pk_bf16_f32 v64, v68, v69
	v_cvt_pk_bf16_f32 v65, v70, v71
	v_cvt_pk_bf16_f32 v66, v72, v73
	v_cvt_pk_bf16_f32 v67, v74, v75
	flat_store_dwordx4 v[80:81], v[64:67] offset:256
	v_mov_b32_e32 v70, v217
	v_mul_f32_e32 v56, v56, v70
	v_mul_f32_e32 v57, v57, v70
	v_max_f32_e32 v56, 0, v56
	v_max_f32_e32 v57, 0, v57
	v_mul_f32_e32 v60, v60, v70
	v_mul_f32_e32 v61, v61, v70
	v_pk_mul_f32 v[66:67], v[56:57], v[56:57]
	v_mul_f32_e32 v57, v58, v70
	v_max_f32_e32 v60, 0, v60
	v_max_f32_e32 v61, 0, v61
	v_mul_f32_e32 v56, v62, v70
	v_max_f32_e32 v58, 0, v57
	v_mul_f32_e32 v57, v63, v70
	v_mul_f32_e32 v59, v59, v70
	v_lshl_add_u64 v[64:65], v[138:139], 0, s[0:1]
	v_pk_mul_f32 v[60:61], v[60:61], v[60:61]
	v_max_f32_e32 v56, 0, v56
	v_max_f32_e32 v57, 0, v57
	v_max_f32_e32 v59, 0, v59
	s_mov_b32 s0, 0x100000
	v_pk_mul_f32 v[62:63], v[56:57], v[56:57]
	v_pk_mul_f32 v[68:69], v[58:59], v[58:59]
	v_cvt_pk_bf16_f32 v56, v60, v61
	v_add_co_u32_e32 v60, vcc, s0, v138
	v_mul_f32_e32 v48, v48, v70
	v_mul_f32_e32 v49, v49, v70
	v_cvt_pk_bf16_f32 v57, v62, v63
	v_cvt_pk_bf16_f32 v58, v66, v67
	v_cvt_pk_bf16_f32 v59, v68, v69
	v_addc_co_u32_e32 v61, vcc, 0, v139, vcc
	v_max_f32_e32 v48, 0, v48
	v_max_f32_e32 v49, 0, v49
	flat_store_dwordx4 v[60:61], v[56:59]
	v_mul_f32_e32 v52, v52, v70
	v_mul_f32_e32 v53, v53, v70
	v_pk_mul_f32 v[56:57], v[48:49], v[48:49]
	v_mul_f32_e32 v49, v50, v70
	v_mul_f32_e32 v48, v54, v70
	v_max_f32_e32 v50, 0, v49
	v_mul_f32_e32 v49, v55, v70
	v_mul_f32_e32 v51, v51, v70
	v_max_f32_e32 v52, 0, v52
	v_max_f32_e32 v53, 0, v53
	v_max_f32_e32 v48, 0, v48
	v_max_f32_e32 v49, 0, v49
	v_max_f32_e32 v51, 0, v51
	v_pk_mul_f32 v[52:53], v[52:53], v[52:53]
	v_pk_mul_f32 v[54:55], v[48:49], v[48:49]
	v_pk_mul_f32 v[58:59], v[50:51], v[50:51]
	v_cvt_pk_bf16_f32 v48, v52, v53
	v_cvt_pk_bf16_f32 v49, v54, v55
	v_cvt_pk_bf16_f32 v50, v56, v57
	v_cvt_pk_bf16_f32 v51, v58, v59
	flat_store_dwordx4 v[64:65], v[48:51] offset:256
	v_mov_b32_e32 v54, v218
	s_mov_b64 s[0:1], 0x120000
	v_lshl_add_u64 v[48:49], v[138:139], 0, s[0:1]
	s_mov_b32 s0, 0x120000
	v_mul_f32_e32 v40, v40, v54
	v_mul_f32_e32 v41, v41, v54
	v_max_f32_e32 v40, 0, v40
	v_max_f32_e32 v41, 0, v41
	v_mul_f32_e32 v44, v44, v54
	v_mul_f32_e32 v45, v45, v54
	v_pk_mul_f32 v[50:51], v[40:41], v[40:41]
	v_mul_f32_e32 v41, v42, v54
	v_max_f32_e32 v44, 0, v44
	v_max_f32_e32 v45, 0, v45
; __device__ __forceinline__ unsigned pk2(float lo, float hi) { f32x2 v = {lo, hi}; bf16x2_t b = __builtin_convertvector(v, bf16x2_t); return __builtin_bit_cast(unsigned, b); }
;     __device__ __forceinline__ void operator()(const f32x4 (&acc)[2][2][4][2], const Unit& u, int wr, int wc, int fr, int fq) const {
;     ...
;             for (int m = 0; m < 4; ++m) { bf16_t* rowp = O + (size_t)(row0 + ai * HALF + m * 16) * ldc + col0; float rsv = 1.f; if (ACT == 1) rsv = rs[row0 + ai * HALF + m * 16];
; #pragma unroll
;                 for (int bj = 0; bj < 2; ++bj) { f32x4 v0 = acc[ai][bj][m][0], v1 = acc[ai][bj][m][1];
;                     if (ACT == 1) {
; #pragma unroll
;                         for (int j = 0; j < 4; ++j) { const float a = fmaxf(v0[j] * rsv, 0.f), b = fmaxf(v1[j] * rsv, 0.f); v0[j] = a * a; v1[j] = b * b; } }
;                     u32x4 w; w.x = pk2(v0[0], v0[1]); w.y = pk2(v0[2], v0[3]); w.z = pk2(v1[0], v1[1]); w.w = pk2(v1[2], v1[3]);
;                     *(u32x4*)(rowp + bj * HALF) = w; } }
; template <class Epi, class Sched, bool ALIGN_EPI = false, bool SP2 = false>
; __device__ __forceinline__ void gemm_phase(PG8_LAS unsigned char* lds, const Gemm g, const Sched& S, const Epi& E) {
;     ...
;         if (!has_next) break;
; #pragma unroll
;         for (int a = 0; a < 2; ++a)
; #pragma unroll
;             for (int b = 0; b < 2; ++b)
; #pragma unroll
;                 for (int m = 0; m < 4; ++m)
; #pragma unroll
;                     for (int n = 0; n < 2; ++n) acc[a][b][m][n] = (f32x4){0.f, 0.f, 0.f, 0.f};
	v_mul_f32_e32 v40, v46, v54
	v_max_f32_e32 v42, 0, v41
	v_mul_f32_e32 v41, v47, v54
	v_mul_f32_e32 v43, v43, v54
	v_pk_mul_f32 v[44:45], v[44:45], v[44:45]
	v_max_f32_e32 v40, 0, v40
	v_max_f32_e32 v41, 0, v41
	v_max_f32_e32 v43, 0, v43
	v_pk_mul_f32 v[46:47], v[40:41], v[40:41]
	v_pk_mul_f32 v[52:53], v[42:43], v[42:43]
	v_cvt_pk_bf16_f32 v40, v44, v45
	v_add_co_u32_e32 v44, vcc, s0, v138
	v_mul_f32_e32 v32, v32, v54
	v_mul_f32_e32 v33, v33, v54
	v_cvt_pk_bf16_f32 v41, v46, v47
	v_cvt_pk_bf16_f32 v42, v50, v51
	v_cvt_pk_bf16_f32 v43, v52, v53
	v_addc_co_u32_e32 v45, vcc, 0, v139, vcc
	v_max_f32_e32 v32, 0, v32
	v_max_f32_e32 v33, 0, v33
	flat_store_dwordx4 v[44:45], v[40:43]
	v_mul_f32_e32 v36, v36, v54
	v_mul_f32_e32 v37, v37, v54
	v_pk_mul_f32 v[40:41], v[32:33], v[32:33]
	v_mul_f32_e32 v33, v34, v54
	v_mul_f32_e32 v32, v38, v54
	v_max_f32_e32 v34, 0, v33
	v_mul_f32_e32 v33, v39, v54
	v_mul_f32_e32 v35, v35, v54
	v_max_f32_e32 v36, 0, v36
	v_max_f32_e32 v37, 0, v37
	v_max_f32_e32 v32, 0, v32
	v_max_f32_e32 v33, 0, v33
	v_max_f32_e32 v35, 0, v35
	v_pk_mul_f32 v[36:37], v[36:37], v[36:37]
	v_pk_mul_f32 v[38:39], v[32:33], v[32:33]
	v_pk_mul_f32 v[42:43], v[34:35], v[34:35]
	v_cvt_pk_bf16_f32 v32, v36, v37
	v_cvt_pk_bf16_f32 v33, v38, v39
	v_cvt_pk_bf16_f32 v34, v40, v41
	v_cvt_pk_bf16_f32 v35, v42, v43
	flat_store_dwordx4 v[48:49], v[32:35] offset:256
	v_mov_b32_e32 v38, v219
	s_mov_b64 s[0:1], 0x140000
	v_lshl_add_u64 v[32:33], v[138:139], 0, s[0:1]
	s_mov_b32 s0, 0x140000
	v_mul_f32_e32 v24, v24, v38
	v_mul_f32_e32 v25, v25, v38
	v_max_f32_e32 v24, 0, v24
	v_max_f32_e32 v25, 0, v25
	v_mul_f32_e32 v28, v28, v38
	v_mul_f32_e32 v29, v29, v38
	v_pk_mul_f32 v[34:35], v[24:25], v[24:25]
	v_mul_f32_e32 v25, v26, v38
	v_max_f32_e32 v28, 0, v28
	v_max_f32_e32 v29, 0, v29
	v_mul_f32_e32 v24, v30, v38
	v_max_f32_e32 v26, 0, v25
	v_mul_f32_e32 v25, v31, v38
	v_mul_f32_e32 v27, v27, v38
	v_pk_mul_f32 v[28:29], v[28:29], v[28:29]
	v_max_f32_e32 v24, 0, v24
	v_max_f32_e32 v25, 0, v25
	v_max_f32_e32 v27, 0, v27
	v_pk_mul_f32 v[30:31], v[24:25], v[24:25]
	v_pk_mul_f32 v[36:37], v[26:27], v[26:27]
	v_cvt_pk_bf16_f32 v24, v28, v29
	v_add_co_u32_e32 v28, vcc, s0, v138
	v_mul_f32_e32 v16, v16, v38
	v_mul_f32_e32 v17, v17, v38
	v_cvt_pk_bf16_f32 v25, v30, v31
	v_cvt_pk_bf16_f32 v26, v34, v35
	v_cvt_pk_bf16_f32 v27, v36, v37
	v_addc_co_u32_e32 v29, vcc, 0, v139, vcc
	v_max_f32_e32 v16, 0, v16
	v_max_f32_e32 v17, 0, v17
	flat_store_dwordx4 v[28:29], v[24:27]
	v_mul_f32_e32 v20, v20, v38
	v_mul_f32_e32 v21, v21, v38
	v_pk_mul_f32 v[24:25], v[16:17], v[16:17]
	v_mul_f32_e32 v17, v18, v38
	v_mul_f32_e32 v16, v22, v38
	v_max_f32_e32 v18, 0, v17
	v_mul_f32_e32 v17, v23, v38
	v_mul_f32_e32 v19, v19, v38
	v_max_f32_e32 v20, 0, v20
	v_max_f32_e32 v21, 0, v21
	v_max_f32_e32 v16, 0, v16
	v_max_f32_e32 v17, 0, v17
	v_max_f32_e32 v19, 0, v19
	v_pk_mul_f32 v[20:21], v[20:21], v[20:21]
	v_pk_mul_f32 v[22:23], v[16:17], v[16:17]
	v_pk_mul_f32 v[26:27], v[18:19], v[18:19]
	v_cvt_pk_bf16_f32 v16, v20, v21
	v_cvt_pk_bf16_f32 v17, v22, v23
	v_cvt_pk_bf16_f32 v18, v24, v25
	v_cvt_pk_bf16_f32 v19, v26, v27
	flat_store_dwordx4 v[32:33], v[16:19] offset:256
	v_mov_b32_e32 v22, v220
	s_mov_b64 s[0:1], 0x160000
	v_lshl_add_u64 v[16:17], v[138:139], 0, s[0:1]
	s_mov_b32 s0, 0x160000
	v_mul_f32_e32 v8, v8, v22
	v_mul_f32_e32 v9, v9, v22
	v_max_f32_e32 v8, 0, v8
	v_max_f32_e32 v9, 0, v9
	v_mul_f32_e32 v12, v12, v22
	v_mul_f32_e32 v13, v13, v22
	v_pk_mul_f32 v[18:19], v[8:9], v[8:9]
	v_mul_f32_e32 v9, v10, v22
	v_max_f32_e32 v12, 0, v12
	v_max_f32_e32 v13, 0, v13
	v_mul_f32_e32 v8, v14, v22
	v_max_f32_e32 v10, 0, v9
	v_mul_f32_e32 v9, v15, v22
	v_mul_f32_e32 v11, v11, v22
	v_pk_mul_f32 v[12:13], v[12:13], v[12:13]
	v_max_f32_e32 v8, 0, v8
	v_max_f32_e32 v9, 0, v9
	v_max_f32_e32 v11, 0, v11
	v_pk_mul_f32 v[14:15], v[8:9], v[8:9]
	v_pk_mul_f32 v[20:21], v[10:11], v[10:11]
	v_cvt_pk_bf16_f32 v8, v12, v13
	v_add_co_u32_e32 v12, vcc, s0, v138
	v_mul_f32_e32 v0, v0, v22
	v_mul_f32_e32 v1, v1, v22
	v_cvt_pk_bf16_f32 v9, v14, v15
	v_cvt_pk_bf16_f32 v10, v18, v19
	v_cvt_pk_bf16_f32 v11, v20, v21
	v_addc_co_u32_e32 v13, vcc, 0, v139, vcc
	v_max_f32_e32 v0, 0, v0
	v_max_f32_e32 v1, 0, v1
	flat_store_dwordx4 v[12:13], v[8:11]
	v_mul_f32_e32 v4, v4, v22
	v_mul_f32_e32 v5, v5, v22
	v_pk_mul_f32 v[8:9], v[0:1], v[0:1]
	v_mul_f32_e32 v1, v2, v22
	v_mul_f32_e32 v0, v6, v22
	v_max_f32_e32 v2, 0, v1
	v_mul_f32_e32 v1, v7, v22
	v_mul_f32_e32 v3, v3, v22
	v_max_f32_e32 v4, 0, v4
	v_max_f32_e32 v5, 0, v5
	v_max_f32_e32 v0, 0, v0
	v_max_f32_e32 v1, 0, v1
	v_max_f32_e32 v3, 0, v3
	v_pk_mul_f32 v[4:5], v[4:5], v[4:5]
	v_pk_mul_f32 v[6:7], v[0:1], v[0:1]
	v_pk_mul_f32 v[10:11], v[2:3], v[2:3]
	v_cvt_pk_bf16_f32 v0, v4, v5
	v_cvt_pk_bf16_f32 v1, v6, v7
	v_cvt_pk_bf16_f32 v2, v8, v9
	v_cvt_pk_bf16_f32 v3, v10, v11
	s_andn2_b64 vcc, exec, s[38:39]
	flat_store_dwordx4 v[16:17], v[0:3] offset:256
	s_cbranch_vccnz .LBB0_1214
	s_andn2_b64 vcc, exec, s[30:31]
	s_cbranch_vccnz .LBB0_1213
	s_barrier
	s_branch .LBB0_1213
